# speedup vs baseline: 1.0011x; 1.0011x over previous
.LBB0_1289:
	s_or_b64 exec, exec, s[4:5]
	s_waitcnt lgkmcnt(0)
	v_mov_b32_e32 v0, 0
	s_barrier
	s_add_u32 s22, s14, 0x6000
	v_mbcnt_lo_u32_b32 v0, -1, v0
	v_mbcnt_hi_u32_b32 v0, -1, v0
	v_add_u32_e32 v0, s33, v0
	v_mov_b32_e32 v129, 0
	s_addc_u32 s23, s15, 0
	v_cmp_eq_u32_e64 s[4:5], 0, v0
	s_mov_b32 s25, 0
	s_movk_i32 s35, 0x3ff
	s_mov_b32 s92, 0
	s_mov_b32 s46, 0x42fc0000
	s_movk_i32 s47, 0x300
	s_mov_b64 s[26:27], 0x2000
	s_add_i32 s48, 0, 0x12000
	s_mov_b32 s49, 0xf149f2ca
	v_mov_b32_e32 v136, 0x42800000
	v_mov_b32_e32 v137, 0x3fff
	v_mov_b32_e32 v138, 0xf149f2ca
	s_branch .LBB0_1293
.LBB0_1290:
	s_or_b64 exec, exec, s[8:9]
	s_mov_b64 s[94:95], exec
	s_mov_b64 exec, s[4:5]
	v_mov_b32_e32 v251, 1
	global_atomic_add v251, v129, v251, s[22:23] sc0
	s_mov_b64 exec, s[94:95]
	s_mov_b32 s92, 1
	v_add_u32_e32 v68, s39, v128
	ds_read_b128 v[64:67], v68
	s_mulk_i32 s41, 0x2200
	s_add_i32 s6, s41, 0
	v_lshlrev_b32_e32 v69, 1, v142
	v_mul_u32_u24_e32 v70, 0x440, v143
	s_waitcnt lgkmcnt(0)
	v_mul_f32_e32 v0, v0, v64
	v_add3_u32 v69, s6, v69, v70
	v_cvt_pk_bf16_f32 v0, v0, v129
	ds_write_b16 v69, v0
	v_mul_f32_e32 v0, v48, v64
	v_cvt_pk_bf16_f32 v0, v0, v129
	ds_write_b16 v69, v0 offset:64
	v_mul_f32_e32 v0, v32, v64
	v_cvt_pk_bf16_f32 v0, v0, v129
	ds_write_b16 v69, v0 offset:128
	v_mul_f32_e32 v0, v16, v64
	v_cvt_pk_bf16_f32 v0, v0, v129
	ds_write_b16 v69, v0 offset:192
	v_mul_f32_e32 v0, v1, v65
	v_cvt_pk_bf16_f32 v0, v0, v129
	ds_write_b16 v69, v0 offset:272
	v_mul_f32_e32 v0, v49, v65
	v_cvt_pk_bf16_f32 v0, v0, v129
	ds_write_b16 v69, v0 offset:336
	v_mul_f32_e32 v0, v33, v65
	v_cvt_pk_bf16_f32 v0, v0, v129
	ds_write_b16 v69, v0 offset:400
	v_mul_f32_e32 v0, v17, v65
	v_cvt_pk_bf16_f32 v0, v0, v129
	ds_write_b16 v69, v0 offset:464
	v_mul_f32_e32 v0, v2, v66
	v_cvt_pk_bf16_f32 v0, v0, v129
	ds_write_b16 v69, v0 offset:544
	v_mul_f32_e32 v0, v50, v66
	v_cvt_pk_bf16_f32 v0, v0, v129
	ds_write_b16 v69, v0 offset:608
	v_mul_f32_e32 v0, v34, v66
	v_cvt_pk_bf16_f32 v0, v0, v129
	ds_write_b16 v69, v0 offset:672
	v_mul_f32_e32 v0, v18, v66
	v_cvt_pk_bf16_f32 v0, v0, v129
	ds_write_b16 v69, v0 offset:736
	v_mul_f32_e32 v0, v3, v67
	v_cvt_pk_bf16_f32 v0, v0, v129
	ds_write_b16 v69, v0 offset:816
	v_mul_f32_e32 v0, v51, v67
	v_cvt_pk_bf16_f32 v0, v0, v129
	ds_write_b16 v69, v0 offset:880
	v_mul_f32_e32 v0, v35, v67
	v_cvt_pk_bf16_f32 v0, v0, v129
	ds_write_b16 v69, v0 offset:944
	v_mul_f32_e32 v0, v19, v67
	v_cvt_pk_bf16_f32 v0, v0, v129
	ds_write_b16 v69, v0 offset:1008
	ds_read_b128 v[0:3], v68 offset:32
	s_waitcnt lgkmcnt(0)
	v_mul_f32_e32 v4, v4, v0
	v_cvt_pk_bf16_f32 v4, v4, v129
	ds_write_b16 v69, v4 offset:2176
	v_mul_f32_e32 v4, v52, v0
	v_cvt_pk_bf16_f32 v4, v4, v129
	ds_write_b16 v69, v4 offset:2240
	v_mul_f32_e32 v4, v36, v0
	v_mul_f32_e32 v0, v20, v0
	v_cvt_pk_bf16_f32 v4, v4, v129
	ds_write_b16 v69, v4 offset:2304
	v_cvt_pk_bf16_f32 v0, v0, v129
	ds_write_b16 v69, v0 offset:2368
	v_mul_f32_e32 v0, v5, v1
	v_cvt_pk_bf16_f32 v0, v0, v129
	ds_write_b16 v69, v0 offset:2448
	v_mul_f32_e32 v0, v53, v1
	v_cvt_pk_bf16_f32 v0, v0, v129
	ds_write_b16 v69, v0 offset:2512
	v_mul_f32_e32 v0, v37, v1
	v_cvt_pk_bf16_f32 v0, v0, v129
	ds_write_b16 v69, v0 offset:2576
	v_mul_f32_e32 v0, v21, v1
	v_cvt_pk_bf16_f32 v0, v0, v129
	ds_write_b16 v69, v0 offset:2640
	v_mul_f32_e32 v0, v6, v2
	v_cvt_pk_bf16_f32 v0, v0, v129
	ds_write_b16 v69, v0 offset:2720
	v_mul_f32_e32 v0, v54, v2
	v_cvt_pk_bf16_f32 v0, v0, v129
	ds_write_b16 v69, v0 offset:2784
	v_mul_f32_e32 v0, v38, v2
	v_cvt_pk_bf16_f32 v0, v0, v129
	ds_write_b16 v69, v0 offset:2848
	v_mul_f32_e32 v0, v22, v2
	v_cvt_pk_bf16_f32 v0, v0, v129
	ds_write_b16 v69, v0 offset:2912
	v_mul_f32_e32 v0, v7, v3
	v_cvt_pk_bf16_f32 v0, v0, v129
	ds_write_b16 v69, v0 offset:2992
	v_mul_f32_e32 v0, v55, v3
	v_cvt_pk_bf16_f32 v0, v0, v129
	ds_write_b16 v69, v0 offset:3056
	v_mul_f32_e32 v0, v39, v3
	v_cvt_pk_bf16_f32 v0, v0, v129
	ds_write_b16 v69, v0 offset:3120
	v_mul_f32_e32 v0, v23, v3
	v_cvt_pk_bf16_f32 v0, v0, v129
	ds_write_b16 v69, v0 offset:3184
	ds_read_b128 v[0:3], v68 offset:64
	s_waitcnt lgkmcnt(0)
	v_mul_f32_e32 v4, v8, v0
	v_cvt_pk_bf16_f32 v4, v4, v129
	ds_write_b16 v69, v4 offset:4352
	v_mul_f32_e32 v4, v56, v0
	v_cvt_pk_bf16_f32 v4, v4, v129
	ds_write_b16 v69, v4 offset:4416
	v_mul_f32_e32 v4, v40, v0
	v_mul_f32_e32 v0, v24, v0
	v_cvt_pk_bf16_f32 v4, v4, v129
	ds_write_b16 v69, v4 offset:4480
	v_cvt_pk_bf16_f32 v0, v0, v129
	ds_write_b16 v69, v0 offset:4544
	v_mul_f32_e32 v0, v9, v1
	v_cvt_pk_bf16_f32 v0, v0, v129
	ds_write_b16 v69, v0 offset:4624
	v_mul_f32_e32 v0, v57, v1
	v_cvt_pk_bf16_f32 v0, v0, v129
	ds_write_b16 v69, v0 offset:4688
	v_mul_f32_e32 v0, v41, v1
	v_cvt_pk_bf16_f32 v0, v0, v129
	ds_write_b16 v69, v0 offset:4752
	v_mul_f32_e32 v0, v25, v1
	v_cvt_pk_bf16_f32 v0, v0, v129
	ds_write_b16 v69, v0 offset:4816
	v_mul_f32_e32 v0, v10, v2
	v_cvt_pk_bf16_f32 v0, v0, v129
	ds_write_b16 v69, v0 offset:4896
	v_mul_f32_e32 v0, v58, v2
	v_cvt_pk_bf16_f32 v0, v0, v129
	ds_write_b16 v69, v0 offset:4960
	v_mul_f32_e32 v0, v42, v2
	v_cvt_pk_bf16_f32 v0, v0, v129
	ds_write_b16 v69, v0 offset:5024
	v_mul_f32_e32 v0, v26, v2
	v_cvt_pk_bf16_f32 v0, v0, v129
	ds_write_b16 v69, v0 offset:5088
	v_mul_f32_e32 v0, v11, v3
	v_cvt_pk_bf16_f32 v0, v0, v129
	ds_write_b16 v69, v0 offset:5168
	v_mul_f32_e32 v0, v59, v3
	v_cvt_pk_bf16_f32 v0, v0, v129
	ds_write_b16 v69, v0 offset:5232
	v_mul_f32_e32 v0, v43, v3
	v_cvt_pk_bf16_f32 v0, v0, v129
	ds_write_b16 v69, v0 offset:5296
	v_mul_f32_e32 v0, v27, v3
	v_cvt_pk_bf16_f32 v0, v0, v129
	ds_write_b16 v69, v0 offset:5360
	ds_read_b128 v[0:3], v68 offset:96
	s_waitcnt lgkmcnt(0)
	v_mul_f32_e32 v4, v12, v0
	v_cvt_pk_bf16_f32 v4, v4, v129
	ds_write_b16 v69, v4 offset:6528
	v_mul_f32_e32 v4, v60, v0
	v_cvt_pk_bf16_f32 v4, v4, v129
	ds_write_b16 v69, v4 offset:6592
	v_mul_f32_e32 v4, v44, v0
	v_mul_f32_e32 v0, v28, v0
	v_cvt_pk_bf16_f32 v4, v4, v129
	ds_write_b16 v69, v4 offset:6656
	v_cvt_pk_bf16_f32 v0, v0, v129
	ds_write_b16 v69, v0 offset:6720
	v_mul_f32_e32 v0, v13, v1
	v_cvt_pk_bf16_f32 v0, v0, v129
	ds_write_b16 v69, v0 offset:6800
	v_mul_f32_e32 v0, v61, v1
	v_cvt_pk_bf16_f32 v0, v0, v129
	ds_write_b16 v69, v0 offset:6864
	v_mul_f32_e32 v0, v45, v1
	v_cvt_pk_bf16_f32 v0, v0, v129
	ds_write_b16 v69, v0 offset:6928
	v_mul_f32_e32 v0, v29, v1
	v_cvt_pk_bf16_f32 v0, v0, v129
	ds_write_b16 v69, v0 offset:6992
	v_mul_f32_e32 v0, v14, v2
	v_cvt_pk_bf16_f32 v0, v0, v129
	ds_write_b16 v69, v0 offset:7072
	v_mul_f32_e32 v0, v62, v2
	v_cvt_pk_bf16_f32 v0, v0, v129
	ds_write_b16 v69, v0 offset:7136
	v_mul_f32_e32 v0, v46, v2
	v_cvt_pk_bf16_f32 v0, v0, v129
	ds_write_b16 v69, v0 offset:7200
	v_mul_f32_e32 v0, v30, v2
	v_cvt_pk_bf16_f32 v0, v0, v129
	ds_write_b16 v69, v0 offset:7264
	v_mul_f32_e32 v0, v15, v3
	v_cvt_pk_bf16_f32 v0, v0, v129
	ds_write_b16 v69, v0 offset:7344
	v_mul_f32_e32 v0, v63, v3
	v_cvt_pk_bf16_f32 v0, v0, v129
	ds_write_b16 v69, v0 offset:7408
	v_mul_f32_e32 v0, v47, v3
	v_cvt_pk_bf16_f32 v0, v0, v129
	ds_write_b16 v69, v0 offset:7472
	v_mul_f32_e32 v0, v31, v3
	v_cvt_pk_bf16_f32 v0, v0, v129
	ds_write_b16 v69, v0 offset:7536
	v_lshlrev_b32_e32 v0, 4, v141
	v_lshrrev_b32_e32 v4, 4, v140
	v_and_b32_e32 v128, 0xf0, v0
	v_mul_u32_u24_e32 v0, 0x110, v4
	s_waitcnt lgkmcnt(0)
	v_add3_u32 v14, s6, v128, v0
	ds_read_b128 v[0:3], v14
	v_or_b32_e32 v10, s40, v4
	v_ashrrev_i32_e32 v11, 31, v10
	v_lshl_add_u64 v[8:9], s[28:29], 0, v[128:129]
	v_lshlrev_b64 v[4:5], 12, v[10:11]
	v_lshl_add_u64 v[12:13], v[8:9], 0, v[4:5]
	ds_read_b128 v[4:7], v14 offset:1088
	s_waitcnt lgkmcnt(0)
	global_store_dwordx4 v[12:13], v[0:3], off
	s_nop 1
	v_or_b32_e32 v0, 4, v10
	v_ashrrev_i32_e32 v1, 31, v0
	v_lshlrev_b64 v[0:1], 12, v[0:1]
	v_lshl_add_u64 v[0:1], v[8:9], 0, v[0:1]
	global_store_dwordx4 v[0:1], v[4:7], off
	ds_read_b128 v[0:3], v14 offset:2176
	s_nop 0
	v_or_b32_e32 v4, 8, v10
	v_ashrrev_i32_e32 v5, 31, v4
	v_lshlrev_b64 v[4:5], 12, v[4:5]
	v_lshl_add_u64 v[12:13], v[8:9], 0, v[4:5]
	ds_read_b128 v[4:7], v14 offset:3264
	s_waitcnt lgkmcnt(0)
	global_store_dwordx4 v[12:13], v[0:3], off
	s_nop 1
	v_or_b32_e32 v0, 12, v10
	v_ashrrev_i32_e32 v1, 31, v0
	v_lshlrev_b64 v[0:1], 12, v[0:1]
	v_lshl_add_u64 v[0:1], v[8:9], 0, v[0:1]
	global_store_dwordx4 v[0:1], v[4:7], off
	ds_read_b128 v[0:3], v14 offset:4352
	s_nop 0
	v_or_b32_e32 v4, 16, v10
	v_ashrrev_i32_e32 v5, 31, v4
	v_lshlrev_b64 v[4:5], 12, v[4:5]
	v_lshl_add_u64 v[12:13], v[8:9], 0, v[4:5]
	ds_read_b128 v[4:7], v14 offset:5440
	s_waitcnt lgkmcnt(0)
	global_store_dwordx4 v[12:13], v[0:3], off
	s_nop 1
	v_or_b32_e32 v0, 20, v10
	v_ashrrev_i32_e32 v1, 31, v0
	v_lshlrev_b64 v[0:1], 12, v[0:1]
	v_lshl_add_u64 v[0:1], v[8:9], 0, v[0:1]
	global_store_dwordx4 v[0:1], v[4:7], off
	ds_read_b128 v[0:3], v14 offset:6528
	s_nop 0
	v_or_b32_e32 v4, 24, v10
	v_ashrrev_i32_e32 v5, 31, v4
	v_lshlrev_b64 v[4:5], 12, v[4:5]
	v_lshl_add_u64 v[12:13], v[8:9], 0, v[4:5]
	ds_read_b128 v[4:7], v14 offset:7616
	s_waitcnt lgkmcnt(0)
	global_store_dwordx4 v[12:13], v[0:3], off
	s_nop 1
	v_or_b32_e32 v0, 28, v10
	v_ashrrev_i32_e32 v1, 31, v0
	v_lshlrev_b64 v[0:1], 12, v[0:1]
	v_lshl_add_u64 v[0:1], v[8:9], 0, v[0:1]
	global_store_dwordx4 v[0:1], v[4:7], off
	s_waitcnt vmcnt(0) lgkmcnt(0)
	s_barrier

.LBB0_1293:
	s_mov_b32 s24, 0x23f00
	s_and_saveexec_b64 s[6:7], s[4:5]
	s_cbranch_execz .LBB0_1297
	s_mov_b64 s[10:11], exec
	v_mbcnt_lo_u32_b32 v0, s10, 0
	v_mbcnt_hi_u32_b32 v0, s11, v0
	v_cmp_eq_u32_e32 vcc, 0, v0
	s_and_saveexec_b64 s[8:9], vcc
	s_cbranch_execz .LBB0_1296
	s_cmp_lg_u32 s92, 0
	s_cbranch_scc1 .Lq_have
	s_bcnt1_i32_b64 s10, s[10:11]
	v_mov_b32_e32 v1, s10
	global_atomic_add v1, v129, v1, s[22:23] sc0
	s_branch .Lq_got
.Lq_have:
	v_mov_b32_e32 v1, v251
.Lq_got:
.LBB0_1296:
	s_or_b64 exec, exec, s[8:9]
	s_waitcnt vmcnt(0)
	v_readfirstlane_b32 s8, v1
	s_nop 1
	v_add_u32_e32 v0, s8, v0
	s_add_i32 s8, s24, 0
	v_mov_b32_e32 v1, s8
	ds_write_b32 v1, v0

.LBB0_1405:
	s_or_b64 exec, exec, s[8:9]
	s_mov_b64 s[94:95], exec
	s_mov_b64 exec, s[4:5]
	v_mov_b32_e32 v251, 1
	global_atomic_add v251, v129, v251, s[22:23] sc0
	s_mov_b64 exec, s[94:95]
	s_mov_b32 s92, 1
	v_add_u32_e32 v68, s70, v128
	ds_read_b128 v[64:67], v68
	s_mulk_i32 s53, 0x2200
	s_add_i32 s6, s53, 0
	v_lshlrev_b32_e32 v69, 1, v142
	v_mul_u32_u24_e32 v70, 0x440, v143
	s_waitcnt lgkmcnt(0)
	v_mul_f32_e32 v0, v0, v64
	v_add3_u32 v69, s6, v69, v70
	v_cvt_pk_bf16_f32 v0, v0, v129
	ds_write_b16 v69, v0
	v_mul_f32_e32 v0, v48, v64
	v_cvt_pk_bf16_f32 v0, v0, v129
	ds_write_b16 v69, v0 offset:64
	v_mul_f32_e32 v0, v32, v64
	v_cvt_pk_bf16_f32 v0, v0, v129
	ds_write_b16 v69, v0 offset:128
	v_mul_f32_e32 v0, v16, v64
	v_cvt_pk_bf16_f32 v0, v0, v129
	ds_write_b16 v69, v0 offset:192
	v_mul_f32_e32 v0, v1, v65
	v_cvt_pk_bf16_f32 v0, v0, v129
	ds_write_b16 v69, v0 offset:272
	v_mul_f32_e32 v0, v49, v65
	v_cvt_pk_bf16_f32 v0, v0, v129
	ds_write_b16 v69, v0 offset:336
	v_mul_f32_e32 v0, v33, v65
	v_cvt_pk_bf16_f32 v0, v0, v129
	ds_write_b16 v69, v0 offset:400
	v_mul_f32_e32 v0, v17, v65
	v_cvt_pk_bf16_f32 v0, v0, v129
	ds_write_b16 v69, v0 offset:464
	v_mul_f32_e32 v0, v2, v66
	v_cvt_pk_bf16_f32 v0, v0, v129
	ds_write_b16 v69, v0 offset:544
	v_mul_f32_e32 v0, v50, v66
	v_cvt_pk_bf16_f32 v0, v0, v129
	ds_write_b16 v69, v0 offset:608
	v_mul_f32_e32 v0, v34, v66
	v_cvt_pk_bf16_f32 v0, v0, v129
	ds_write_b16 v69, v0 offset:672
	v_mul_f32_e32 v0, v18, v66
	v_cvt_pk_bf16_f32 v0, v0, v129
	ds_write_b16 v69, v0 offset:736
	v_mul_f32_e32 v0, v3, v67
	v_cvt_pk_bf16_f32 v0, v0, v129
	ds_write_b16 v69, v0 offset:816
	v_mul_f32_e32 v0, v51, v67
	v_cvt_pk_bf16_f32 v0, v0, v129
	ds_write_b16 v69, v0 offset:880
	v_mul_f32_e32 v0, v35, v67
	v_cvt_pk_bf16_f32 v0, v0, v129
	ds_write_b16 v69, v0 offset:944
	v_mul_f32_e32 v0, v19, v67
	v_cvt_pk_bf16_f32 v0, v0, v129
	ds_write_b16 v69, v0 offset:1008
	ds_read_b128 v[0:3], v68 offset:32
	s_waitcnt lgkmcnt(0)
	v_mul_f32_e32 v4, v4, v0
	v_cvt_pk_bf16_f32 v4, v4, v129
	ds_write_b16 v69, v4 offset:2176
	v_mul_f32_e32 v4, v52, v0
	v_cvt_pk_bf16_f32 v4, v4, v129
	ds_write_b16 v69, v4 offset:2240
	v_mul_f32_e32 v4, v36, v0
	v_mul_f32_e32 v0, v20, v0
	v_cvt_pk_bf16_f32 v4, v4, v129
	ds_write_b16 v69, v4 offset:2304
	v_cvt_pk_bf16_f32 v0, v0, v129
	ds_write_b16 v69, v0 offset:2368
	v_mul_f32_e32 v0, v5, v1
	v_cvt_pk_bf16_f32 v0, v0, v129
	ds_write_b16 v69, v0 offset:2448
	v_mul_f32_e32 v0, v53, v1
	v_cvt_pk_bf16_f32 v0, v0, v129
	ds_write_b16 v69, v0 offset:2512
	v_mul_f32_e32 v0, v37, v1
	v_cvt_pk_bf16_f32 v0, v0, v129
	ds_write_b16 v69, v0 offset:2576
	v_mul_f32_e32 v0, v21, v1
	v_cvt_pk_bf16_f32 v0, v0, v129
	ds_write_b16 v69, v0 offset:2640
	v_mul_f32_e32 v0, v6, v2
	v_cvt_pk_bf16_f32 v0, v0, v129
	ds_write_b16 v69, v0 offset:2720
	v_mul_f32_e32 v0, v54, v2
	v_cvt_pk_bf16_f32 v0, v0, v129
	ds_write_b16 v69, v0 offset:2784
	v_mul_f32_e32 v0, v38, v2
	v_cvt_pk_bf16_f32 v0, v0, v129
	ds_write_b16 v69, v0 offset:2848
	v_mul_f32_e32 v0, v22, v2
	v_cvt_pk_bf16_f32 v0, v0, v129
	ds_write_b16 v69, v0 offset:2912
	v_mul_f32_e32 v0, v7, v3
	v_cvt_pk_bf16_f32 v0, v0, v129
	ds_write_b16 v69, v0 offset:2992
	v_mul_f32_e32 v0, v55, v3
	v_cvt_pk_bf16_f32 v0, v0, v129
	ds_write_b16 v69, v0 offset:3056
	v_mul_f32_e32 v0, v39, v3
	v_cvt_pk_bf16_f32 v0, v0, v129
	ds_write_b16 v69, v0 offset:3120
	v_mul_f32_e32 v0, v23, v3
	v_cvt_pk_bf16_f32 v0, v0, v129
	ds_write_b16 v69, v0 offset:3184
	ds_read_b128 v[0:3], v68 offset:64
	s_waitcnt lgkmcnt(0)
	v_mul_f32_e32 v4, v8, v0
	v_cvt_pk_bf16_f32 v4, v4, v129
	ds_write_b16 v69, v4 offset:4352
	v_mul_f32_e32 v4, v56, v0
	v_cvt_pk_bf16_f32 v4, v4, v129
	ds_write_b16 v69, v4 offset:4416
	v_mul_f32_e32 v4, v40, v0
	v_mul_f32_e32 v0, v24, v0
	v_cvt_pk_bf16_f32 v4, v4, v129
	ds_write_b16 v69, v4 offset:4480
	v_cvt_pk_bf16_f32 v0, v0, v129
	ds_write_b16 v69, v0 offset:4544
	v_mul_f32_e32 v0, v9, v1
	v_cvt_pk_bf16_f32 v0, v0, v129
	ds_write_b16 v69, v0 offset:4624
	v_mul_f32_e32 v0, v57, v1
	v_cvt_pk_bf16_f32 v0, v0, v129
	ds_write_b16 v69, v0 offset:4688
	v_mul_f32_e32 v0, v41, v1
	v_cvt_pk_bf16_f32 v0, v0, v129
	ds_write_b16 v69, v0 offset:4752
	v_mul_f32_e32 v0, v25, v1
	v_cvt_pk_bf16_f32 v0, v0, v129
	ds_write_b16 v69, v0 offset:4816
	v_mul_f32_e32 v0, v10, v2
	v_cvt_pk_bf16_f32 v0, v0, v129
	ds_write_b16 v69, v0 offset:4896
	v_mul_f32_e32 v0, v58, v2
	v_cvt_pk_bf16_f32 v0, v0, v129
	ds_write_b16 v69, v0 offset:4960
	v_mul_f32_e32 v0, v42, v2
	v_cvt_pk_bf16_f32 v0, v0, v129
	ds_write_b16 v69, v0 offset:5024
	v_mul_f32_e32 v0, v26, v2
	v_cvt_pk_bf16_f32 v0, v0, v129
	ds_write_b16 v69, v0 offset:5088
	v_mul_f32_e32 v0, v11, v3
	v_cvt_pk_bf16_f32 v0, v0, v129
	ds_write_b16 v69, v0 offset:5168
	v_mul_f32_e32 v0, v59, v3
	v_cvt_pk_bf16_f32 v0, v0, v129
	ds_write_b16 v69, v0 offset:5232
	v_mul_f32_e32 v0, v43, v3
	v_cvt_pk_bf16_f32 v0, v0, v129
	ds_write_b16 v69, v0 offset:5296
	v_mul_f32_e32 v0, v27, v3
	v_cvt_pk_bf16_f32 v0, v0, v129
	ds_write_b16 v69, v0 offset:5360
	ds_read_b128 v[0:3], v68 offset:96
	s_waitcnt lgkmcnt(0)
	v_mul_f32_e32 v4, v12, v0
	v_cvt_pk_bf16_f32 v4, v4, v129
	ds_write_b16 v69, v4 offset:6528
	v_mul_f32_e32 v4, v60, v0
	v_cvt_pk_bf16_f32 v4, v4, v129
	ds_write_b16 v69, v4 offset:6592
	v_mul_f32_e32 v4, v44, v0
	v_mul_f32_e32 v0, v28, v0
	v_cvt_pk_bf16_f32 v4, v4, v129
	ds_write_b16 v69, v4 offset:6656
	v_cvt_pk_bf16_f32 v0, v0, v129
	ds_write_b16 v69, v0 offset:6720
	v_mul_f32_e32 v0, v13, v1
	v_cvt_pk_bf16_f32 v0, v0, v129
	ds_write_b16 v69, v0 offset:6800
	v_mul_f32_e32 v0, v61, v1
	v_cvt_pk_bf16_f32 v0, v0, v129
	ds_write_b16 v69, v0 offset:6864
	v_mul_f32_e32 v0, v45, v1
	v_cvt_pk_bf16_f32 v0, v0, v129
	ds_write_b16 v69, v0 offset:6928
	v_mul_f32_e32 v0, v29, v1
	v_cvt_pk_bf16_f32 v0, v0, v129
	ds_write_b16 v69, v0 offset:6992
	v_mul_f32_e32 v0, v14, v2
	v_cvt_pk_bf16_f32 v0, v0, v129
	ds_write_b16 v69, v0 offset:7072
	v_mul_f32_e32 v0, v62, v2
	v_cvt_pk_bf16_f32 v0, v0, v129
	ds_write_b16 v69, v0 offset:7136
	v_mul_f32_e32 v0, v46, v2
	v_cvt_pk_bf16_f32 v0, v0, v129
	ds_write_b16 v69, v0 offset:7200
	v_mul_f32_e32 v0, v30, v2
	v_cvt_pk_bf16_f32 v0, v0, v129
	ds_write_b16 v69, v0 offset:7264
	v_mul_f32_e32 v0, v15, v3
	v_cvt_pk_bf16_f32 v0, v0, v129
	ds_write_b16 v69, v0 offset:7344
	v_mul_f32_e32 v0, v63, v3
	v_cvt_pk_bf16_f32 v0, v0, v129
	ds_write_b16 v69, v0 offset:7408
	v_mul_f32_e32 v0, v47, v3
	v_cvt_pk_bf16_f32 v0, v0, v129
	ds_write_b16 v69, v0 offset:7472
	v_mul_f32_e32 v0, v31, v3
	v_cvt_pk_bf16_f32 v0, v0, v129
	ds_write_b16 v69, v0 offset:7536
	v_lshlrev_b32_e32 v0, 4, v141
	v_lshrrev_b32_e32 v4, 4, v140
	v_and_b32_e32 v128, 0xf0, v0
	v_mul_u32_u24_e32 v0, 0x110, v4
	s_waitcnt lgkmcnt(0)
	v_add3_u32 v14, s6, v128, v0
	ds_read_b128 v[0:3], v14
	v_or_b32_e32 v10, s52, v4
	v_ashrrev_i32_e32 v11, 31, v10
	v_lshl_add_u64 v[8:9], s[28:29], 0, v[128:129]
	v_lshlrev_b64 v[4:5], 12, v[10:11]
	v_lshl_add_u64 v[12:13], v[8:9], 0, v[4:5]
	ds_read_b128 v[4:7], v14 offset:1088
	s_waitcnt lgkmcnt(0)
	global_store_dwordx4 v[12:13], v[0:3], off
	s_mov_b64 s[6:7], 0
	s_nop 0
	v_or_b32_e32 v0, 4, v10
	v_ashrrev_i32_e32 v1, 31, v0
	v_lshlrev_b64 v[0:1], 12, v[0:1]
	v_lshl_add_u64 v[0:1], v[8:9], 0, v[0:1]
	global_store_dwordx4 v[0:1], v[4:7], off
	ds_read_b128 v[0:3], v14 offset:2176
	s_nop 0
	v_or_b32_e32 v4, 8, v10
	v_ashrrev_i32_e32 v5, 31, v4
	v_lshlrev_b64 v[4:5], 12, v[4:5]
	v_lshl_add_u64 v[12:13], v[8:9], 0, v[4:5]
	ds_read_b128 v[4:7], v14 offset:3264
	s_waitcnt lgkmcnt(0)
	global_store_dwordx4 v[12:13], v[0:3], off
	s_nop 1
	v_or_b32_e32 v0, 12, v10
	v_ashrrev_i32_e32 v1, 31, v0
	v_lshlrev_b64 v[0:1], 12, v[0:1]
	v_lshl_add_u64 v[0:1], v[8:9], 0, v[0:1]
	global_store_dwordx4 v[0:1], v[4:7], off
	ds_read_b128 v[0:3], v14 offset:4352
	s_nop 0
	v_or_b32_e32 v4, 16, v10
	v_ashrrev_i32_e32 v5, 31, v4
	v_lshlrev_b64 v[4:5], 12, v[4:5]
	v_lshl_add_u64 v[12:13], v[8:9], 0, v[4:5]
	ds_read_b128 v[4:7], v14 offset:5440
	s_waitcnt lgkmcnt(0)
	global_store_dwordx4 v[12:13], v[0:3], off
	s_nop 1
	v_or_b32_e32 v0, 20, v10
	v_ashrrev_i32_e32 v1, 31, v0
	v_lshlrev_b64 v[0:1], 12, v[0:1]
	v_lshl_add_u64 v[0:1], v[8:9], 0, v[0:1]
	global_store_dwordx4 v[0:1], v[4:7], off
	ds_read_b128 v[0:3], v14 offset:6528
	s_nop 0
	v_or_b32_e32 v4, 24, v10
	v_ashrrev_i32_e32 v5, 31, v4
	v_lshlrev_b64 v[4:5], 12, v[4:5]
	v_lshl_add_u64 v[12:13], v[8:9], 0, v[4:5]
	ds_read_b128 v[4:7], v14 offset:7616
	s_waitcnt lgkmcnt(0)
	global_store_dwordx4 v[12:13], v[0:3], off
	s_nop 1
	v_or_b32_e32 v0, 28, v10
	v_ashrrev_i32_e32 v1, 31, v0
	v_lshlrev_b64 v[0:1], 12, v[0:1]
	v_lshl_add_u64 v[0:1], v[8:9], 0, v[0:1]
	global_store_dwordx4 v[0:1], v[4:7], off
	s_waitcnt vmcnt(0) lgkmcnt(0)
	s_barrier
